# grid-size guards: the R0 ctx-row spreading and the P1 mods-table spreading apply only on the 256-workgroup grid, any other grid keeps the baseline maps
# speedup vs baseline: 1.0000x; 1.0000x over previous
; __global__ void __launch_bounds__(512, 2) fwd_megakernel(Params Parg) {
;     ...
;         for (int i = bid * 512 + tid; i < 3 * NMOD * D; i += G * 512) {
;             const int ms = i / (NMOD * D), n = i % (NMOD * D); float a = b_mod[n];
; #pragma unroll
;             for (int p = 0; p < 8; ++p) a += part[(p * 3 + ms) * (NMOD * D) + n];
;             mods[i] = a;
;         }
.LBB0_222:
	s_or_b64 exec, exec, s[6:7]
	s_mov_b64 s[8:9], s[0:1]
	s_waitcnt lgkmcnt(0)
	s_barrier
	s_load_dwordx2 s[20:21], s[8:9], 0xd0
	v_mov_b32_e32 v2, v176
	s_load_dwordx2 s[6:7], s[8:9], 0x0
	s_load_dwordx2 s[22:23], s[8:9], 0x28
	v_readfirstlane_b32 s3, v2
	s_waitcnt lgkmcnt(0)
	s_add_u32 s10, s20, 0x3d20000
	s_addc_u32 s11, s21, 0
	s_lshl_b32 s4, s2, 9
	v_writelane_b32 v254, s4, 3
	s_cmp_lg_u32 s28, 0x100
	s_cbranch_scc1 .Lmodtab_orig
	v_and_b32_e32 v0, 63, v2
	v_lshrrev_b32_e32 v1, 6, v2
	v_lshl_add_u32 v0, v1, 14, v0
	s_lshl_b32 s12, s2, 6
	v_add_u32_e32 v0, s12, v0
	s_branch .Lmodtab_join
.Lmodtab_orig:
	v_add_u32_e32 v0, s4, v2
.Lmodtab_join:
	s_movk_i32 s4, 0x6c00
	v_cmp_gt_i32_e32 vcc, s4, v0
	s_and_saveexec_b64 s[14:15], vcc
	s_cbranch_execz .LBB0_225
	s_add_u32 s16, s20, 0x3d00000
	s_addc_u32 s17, s21, 0
	s_lshl_b32 s4, s28, 9
	s_mov_b64 s[18:19], 0
	s_mov_b32 s5, 0x38e38e39
	s_movk_i32 s12, 0x6bff

; __device__ __forceinline__ void unpack8(const u32x4 w, f32x4& a, f32x4& b) { a[0] = bflo(w.x); a[1] = bfhi(w.x); a[2] = bflo(w.y); a[3] = bfhi(w.y); b[0] = bflo(w.z); b[1] = bfhi(w.z); b[2] = bflo(w.w); b[3] = bfhi(w.w); }
; __device__ __forceinline__ void norm_rows_h(const bf16_t* src, bf16_t* dst, int nrows, const f32x4 (&wv)[4], const f32x4 (&shv)[4], int gw, int ngw, int lane) {
;     for (int row0 = gw * 2; row0 < nrows; row0 += ngw * 2) {
;         u32x4 raw[2][2]; f32x4 v[2][4]; float ss[2];
; #pragma unroll
;         for (int rr = 0; rr < 2; ++rr)
; #pragma unroll
;             for (int j = 0; j < 2; ++j) raw[rr][j] = *(const u32x4*)(src + (size_t)(row0 + rr) * D + 8 * lane + 512 * j);
; #pragma unroll
;         for (int rr = 0; rr < 2; ++rr) { float a = 0.f;
; #pragma unroll
;             for (int j = 0; j < 2; ++j) unpack8(raw[rr][j], v[rr][2 * j], v[rr][2 * j + 1]);
; #pragma unroll
;             for (int q = 0; q < 4; ++q) a += (v[rr][q][0] * v[rr][q][0] + v[rr][q][1] * v[rr][q][1]) + (v[rr][q][2] * v[rr][q][2] + v[rr][q][3] * v[rr][q][3]);
;             ss[rr] = a; }
.LBB0_484:
	global_load_dwordx4 v[16:19], v[24:25], off offset:-3072
	global_load_dwordx4 v[38:41], v[24:25], off offset:-2048
	global_load_dwordx4 v[50:53], v[24:25], off offset:-1024
	global_load_dwordx4 v[54:57], v[24:25], off
	s_add_i32 s38, s38, s96
	s_cmpk_lt_i32 s38, 0x4000
	s_waitcnt vmcnt(3)
	v_lshlrev_b32_e32 v74, 16, v16
	v_and_b32_e32 v75, 0xffff0000, v16
	v_mul_f32_e32 v16, v74, v74
	s_waitcnt vmcnt(2)
	v_lshlrev_b32_e32 v42, 16, v40
	v_and_b32_e32 v43, 0xffff0000, v40
	v_lshlrev_b32_e32 v44, 16, v41
	v_and_b32_e32 v45, 0xffff0000, v41
	v_pk_fma_f32 v[40:41], v[74:75], v[74:75], v[16:17] op_sel_hi:[1,1,0]
	v_lshlrev_b32_e32 v16, 16, v17
	v_lshlrev_b32_e32 v77, 16, v19
	v_lshlrev_b32_e32 v76, 16, v18
	v_and_b32_e32 v19, 0xffff0000, v19
	v_and_b32_e32 v18, 0xffff0000, v18
	v_lshlrev_b32_e32 v58, 16, v38
	v_and_b32_e32 v17, 0xffff0000, v17
	v_mul_f32_e32 v46, v16, v16
	v_pk_mul_f32 v[48:49], v[18:19], v[18:19]
	v_and_b32_e32 v59, 0xffff0000, v38
	v_mul_f32_e32 v38, v58, v58
	v_lshlrev_b32_e32 v60, 16, v39
	v_pk_fma_f32 v[46:47], v[16:17], v[16:17], v[46:47] op_sel_hi:[1,1,0]
	v_pk_fma_f32 v[48:49], v[76:77], v[76:77], v[48:49]
	v_pk_fma_f32 v[72:73], v[58:59], v[58:59], v[38:39] op_sel_hi:[1,1,0]
	v_and_b32_e32 v61, 0xffff0000, v39
	v_mul_f32_e32 v38, v60, v60
	v_pk_add_f32 v[48:49], v[48:49], v[48:49] op_sel_hi:[0,1]
	v_pk_fma_f32 v[38:39], v[60:61], v[60:61], v[38:39] op_sel_hi:[1,1,0]
	v_pk_add_f32 v[40:41], v[40:41], v[46:47]
	v_mul_f32_e32 v48, v43, v43
	v_mul_f32_e32 v72, v44, v44
	v_mul_f32_e32 v38, v45, v45
	v_mul_f32_e32 v78, v42, v42
	v_mov_b32_e32 v79, v41
	v_pk_add_f32 v[40:41], v[78:79], v[48:49]
	v_pk_add_f32 v[38:39], v[72:73], v[38:39]
	s_waitcnt vmcnt(1)
	v_lshlrev_b32_e32 v48, 16, v50
	v_pk_add_f32 v[38:39], v[40:41], v[38:39]
	v_and_b32_e32 v49, 0xffff0000, v50
	v_add_f32_e32 v88, v38, v39
	s_waitcnt vmcnt(0)
	v_lshlrev_b32_e32 v38, 16, v56
	v_and_b32_e32 v39, 0xffff0000, v56
	v_mul_f32_e32 v46, v48, v48
	v_lshlrev_b32_e32 v56, 16, v51
	v_lshlrev_b32_e32 v40, 16, v57
	v_and_b32_e32 v41, 0xffff0000, v57
	v_pk_fma_f32 v[72:73], v[48:49], v[48:49], v[46:47] op_sel_hi:[1,1,0]
	v_and_b32_e32 v57, 0xffff0000, v51
	v_mul_f32_e32 v46, v56, v56
	v_lshlrev_b32_e32 v51, 16, v53
	v_lshlrev_b32_e32 v50, 16, v52
	v_and_b32_e32 v53, 0xffff0000, v53
	v_and_b32_e32 v52, 0xffff0000, v52
	v_pk_fma_f32 v[78:79], v[56:57], v[56:57], v[46:47] op_sel_hi:[1,1,0]
	v_pk_mul_f32 v[46:47], v[52:53], v[52:53]
	v_pk_add_f32 v[72:73], v[72:73], v[78:79]
	v_pk_fma_f32 v[46:47], v[50:51], v[50:51], v[46:47]
	v_mul_f32_e32 v86, v38, v38
	v_pk_add_f32 v[80:81], v[46:47], v[46:47] op_sel_hi:[0,1]
	v_lshlrev_b32_e32 v46, 16, v54
	v_and_b32_e32 v47, 0xffff0000, v54
	v_mul_f32_e32 v54, v46, v46
	v_pk_fma_f32 v[82:83], v[46:47], v[46:47], v[54:55] op_sel_hi:[1,1,0]
	v_lshlrev_b32_e32 v54, 16, v55
	v_and_b32_e32 v55, 0xffff0000, v55
	v_mul_f32_e32 v62, v54, v54
	v_pk_fma_f32 v[84:85], v[54:55], v[54:55], v[62:63] op_sel_hi:[1,1,0]
	ds_bpermute_b32 v62, v63, v88
	v_mul_f32_e32 v80, v39, v39
	v_mul_f32_e32 v82, v40, v40
	v_mul_f32_e32 v84, v41, v41
	v_mov_b32_e32 v87, v73
	v_pk_add_f32 v[72:73], v[86:87], v[80:81]
	v_pk_add_f32 v[78:79], v[82:83], v[84:85]
	s_waitcnt lgkmcnt(0)
	v_add_f32_e32 v62, v88, v62
	v_pk_add_f32 v[72:73], v[72:73], v[78:79]
	s_nop 0
	v_add_f32_e32 v72, v72, v73
	ds_bpermute_b32 v73, v64, v62
	s_waitcnt lgkmcnt(0)
	v_add_f32_e32 v62, v62, v73
	ds_bpermute_b32 v73, v65, v62
	s_waitcnt lgkmcnt(0)
	v_add_f32_e32 v62, v62, v73
	ds_bpermute_b32 v73, v66, v62
	s_waitcnt lgkmcnt(0)
	v_add_f32_e32 v62, v62, v73
	ds_bpermute_b32 v73, v70, v62
	s_waitcnt lgkmcnt(0)
	v_add_f32_e32 v62, v62, v73
	ds_bpermute_b32 v73, v71, v62
	s_waitcnt lgkmcnt(0)
; __device__ __forceinline__ u32x4 pack8(const f32x4 a, const f32x4 b) { u32x4 w; w.x = pk2(a[0], a[1]); w.y = pk2(a[2], a[3]); w.z = pk2(b[0], b[1]); w.w = pk2(b[2], b[3]); return w; }
; __device__ __forceinline__ void norm_rows_h(const bf16_t* src, bf16_t* dst, int nrows, const f32x4 (&wv)[4], const f32x4 (&shv)[4], int gw, int ngw, int lane) {
;     ...
; #pragma unroll
;         for (int rr = 0; rr < 2; ++rr) {
;             const float r = rsqrtf(wave_sum(ss[rr], lane) * (1.0f / D) + EPS);
; #pragma unroll
;             for (int j = 0; j < 2; ++j) *(u32x4*)(dst + (size_t)(row0 + rr) * D + 8 * lane + 512 * j) = pack8(v[rr][2 * j] * r * wv[2 * j] + shv[2 * j], v[rr][2 * j + 1] * r * wv[2 * j + 1] + shv[2 * j + 1]);
;         }
;     }
; }
; __device__ __forceinline__ void norm_rows_ctx(const float* cx, const float* slab, bf16_t* dst, int nrows, const f32x4 (&wv)[4], const f32x4 (&shv)[4], int gw, int ngw, int lane) {
;     for (int row = gw; row < nrows; row += ngw) {
	v_add_f32_e32 v62, v62, v73
	v_fmamk_f32 v62, v62, 0x3a800000, v156
	v_cmp_gt_f32_e32 vcc, s13, v62
	v_mul_f32_e32 v73, 0x4b800000, v62
	s_nop 0
	v_cndmask_b32_e32 v62, v62, v73, vcc
	v_rsq_f32_e32 v62, v62
	s_nop 0
	v_mul_f32_e32 v73, 0x45800000, v62
	v_cndmask_b32_e32 v62, v62, v73, vcc
	v_pk_mul_f32 v[74:75], v[62:63], v[74:75] op_sel_hi:[0,1]
	v_pk_mul_f32 v[16:17], v[62:63], v[16:17] op_sel_hi:[0,1]
	v_pk_fma_f32 v[78:79], v[26:27], v[16:17], v[6:7]
	v_pk_fma_f32 v[16:17], v[28:29], v[74:75], v[4:5]
	v_mov_b32_e32 v74, v76
	v_mov_b32_e32 v75, v18
	v_mov_b32_e32 v18, v77
	v_pk_mul_f32 v[74:75], v[62:63], v[74:75] op_sel_hi:[0,1]
	v_pk_mul_f32 v[18:19], v[62:63], v[18:19] op_sel_hi:[0,1]
	v_pk_fma_f32 v[76:77], v[30:31], v[18:19], v[2:3]
	v_pk_fma_f32 v[18:19], v[32:33], v[74:75], v[0:1]
	v_add_co_u32_e32 v74, vcc, s53, v24
	v_cvt_pk_bf16_f32 v16, v16, v17
	v_cvt_pk_bf16_f32 v17, v78, v79
	v_cvt_pk_bf16_f32 v18, v18, v19
	v_cvt_pk_bf16_f32 v19, v76, v77
	s_nop 1
	v_addc_co_u32_e32 v75, vcc, -1, v25, vcc
	global_store_dwordx4 v[74:75], v[16:19], off offset:-3072
	v_pk_mul_f32 v[42:43], v[62:63], v[42:43] op_sel_hi:[0,1]
	v_pk_mul_f32 v[44:45], v[62:63], v[44:45] op_sel_hi:[0,1]
	v_pk_mul_f32 v[16:17], v[62:63], v[58:59] op_sel_hi:[0,1]
	v_pk_mul_f32 v[18:19], v[62:63], v[60:61] op_sel_hi:[0,1]
	v_pk_fma_f32 v[16:17], v[20:21], v[16:17], v[12:13]
	v_pk_fma_f32 v[18:19], v[22:23], v[18:19], v[14:15]
	v_cvt_pk_bf16_f32 v16, v16, v17
	v_pk_fma_f32 v[44:45], v[34:35], v[44:45], v[10:11]
	v_pk_fma_f32 v[42:43], v[36:37], v[42:43], v[8:9]
	v_cvt_pk_bf16_f32 v17, v18, v19
	v_cvt_pk_bf16_f32 v19, v44, v45
	v_mov_b32_e32 v44, v50
	v_cvt_pk_bf16_f32 v18, v42, v43
	global_store_dwordx4 v[74:75], v[16:19], off offset:-2048
	ds_bpermute_b32 v16, v63, v72
	v_mov_b32_e32 v45, v52
	v_mov_b32_e32 v52, v51
	v_lshl_add_u64 v[24:25], v[24:25], 0, s[4:5]
	s_waitcnt lgkmcnt(0)
	v_add_f32_e32 v16, v72, v16
	ds_bpermute_b32 v17, v64, v16
	s_waitcnt lgkmcnt(0)
	v_add_f32_e32 v16, v16, v17
	ds_bpermute_b32 v17, v65, v16
	s_waitcnt lgkmcnt(0)
	v_add_f32_e32 v16, v16, v17
	ds_bpermute_b32 v17, v66, v16
	s_waitcnt lgkmcnt(0)
	v_add_f32_e32 v16, v16, v17
	ds_bpermute_b32 v17, v70, v16
	s_waitcnt lgkmcnt(0)
	v_add_f32_e32 v16, v16, v17
	ds_bpermute_b32 v17, v71, v16
	s_waitcnt lgkmcnt(0)
	v_add_f32_e32 v16, v16, v17
	v_fmamk_f32 v16, v16, 0x3a800000, v156
	v_cmp_gt_f32_e32 vcc, s13, v16
	v_mul_f32_e32 v17, 0x4b800000, v16
	s_nop 0
	v_cndmask_b32_e32 v16, v16, v17, vcc
	v_rsq_f32_e32 v16, v16
	s_nop 0
	v_mul_f32_e32 v17, 0x45800000, v16
	v_cndmask_b32_e32 v42, v16, v17, vcc
	v_pk_mul_f32 v[16:17], v[42:43], v[48:49] op_sel_hi:[0,1]
	v_pk_mul_f32 v[18:19], v[42:43], v[56:57] op_sel_hi:[0,1]
	v_pk_fma_f32 v[18:19], v[26:27], v[18:19], v[6:7]
	v_pk_fma_f32 v[16:17], v[28:29], v[16:17], v[4:5]
	v_pk_mul_f32 v[44:45], v[42:43], v[44:45] op_sel_hi:[0,1]
	v_pk_mul_f32 v[48:49], v[42:43], v[52:53] op_sel_hi:[0,1]
	v_pk_fma_f32 v[48:49], v[30:31], v[48:49], v[2:3]
	v_pk_fma_f32 v[44:45], v[32:33], v[44:45], v[0:1]
	v_cvt_pk_bf16_f32 v16, v16, v17
	v_cvt_pk_bf16_f32 v17, v18, v19
	v_cvt_pk_bf16_f32 v19, v48, v49
	v_pk_mul_f32 v[38:39], v[42:43], v[38:39] op_sel_hi:[0,1]
	v_cvt_pk_bf16_f32 v18, v44, v45
	global_store_dwordx4 v[74:75], v[16:19], off offset:-1024
	v_pk_mul_f32 v[40:41], v[42:43], v[40:41] op_sel_hi:[0,1]
	v_pk_fma_f32 v[40:41], v[34:35], v[40:41], v[10:11]
	v_pk_mul_f32 v[16:17], v[42:43], v[46:47] op_sel_hi:[0,1]
	v_pk_mul_f32 v[18:19], v[42:43], v[54:55] op_sel_hi:[0,1]
	v_pk_fma_f32 v[18:19], v[22:23], v[18:19], v[14:15]
	v_pk_fma_f32 v[16:17], v[20:21], v[16:17], v[12:13]
	v_pk_fma_f32 v[38:39], v[36:37], v[38:39], v[8:9]
	v_cvt_pk_bf16_f32 v16, v16, v17
	v_cvt_pk_bf16_f32 v17, v18, v19
	v_cvt_pk_bf16_f32 v19, v40, v41
	s_nop 0
	v_cvt_pk_bf16_f32 v18, v38, v39
	global_store_dwordx4 v[74:75], v[16:19], off
	s_cbranch_scc1 .LBB0_484
	v_mov_b32_e32 v128, v69
	s_cmp_lg_u32 s28, 0x100
	s_cbranch_scc1 .Lr0sp_skip_0
	s_and_b32 s9, s8, 3
	s_lshr_b32 s8, s8, 2
	s_cmp_lg_u32 s9, 0
	s_cselect_b32 s8, 0x200, s8
.Lr0sp_skip_0:
	s_cmpk_gt_i32 s8, 0x1ff
	s_cbranch_scc1 .LBB0_491
	s_branch .LBB0_489

; __device__ __forceinline__ void norm_rows_ctx(const float* cx, const float* slab, bf16_t* dst, int nrows, const f32x4 (&wv)[4], const f32x4 (&shv)[4], int gw, int ngw, int lane) {
;     for (int row = gw; row < nrows; row += ngw) {
.LBB0_488:
	s_cmp_lg_u32 s28, 0x100
	s_cbranch_scc1 .Lr0sp_skip_1
	s_and_b32 s9, s8, 3
	s_lshr_b32 s8, s8, 2
	s_cmp_lg_u32 s9, 0
	s_cselect_b32 s8, 0x200, s8
